# adds P3 final-epilogue gate loads hoisted up front with counted waits (store-data hazard padded) on top of P6 epilogue hoist + sample PV prefetch
# baseline (speedup 1.0000x reference)
; __device__ __forceinline__ float bf_lo(unsigned w) { return __uint_as_float(w << 16); }
; __device__ __forceinline__ float bf_hi(unsigned w) { return __uint_as_float(w & 0xffff0000u); }
; __device__ __forceinline__ float sigm(float x) { return __builtin_amdgcn_rcpf(1.0f + __builtin_amdgcn_exp2f(-1.4426950408889634f * x)); }
; __device__ __forceinline__ u32x4 pack8(f32x4 a, f32x4 b) { u32x4 w; w.x = cvt_pk_bf16(a[0], a[1]); w.y = cvt_pk_bf16(a[2], a[3]); w.z = cvt_pk_bf16(b[0], b[1]); w.w = cvt_pk_bf16(b[2], b[3]); return w; }
;     __device__ __forceinline__ void operator()(const f32x4 (&acc)[2][2][4][2], const Unit& u, int wr, int wc, int fr, int fq) const {
;         const int row0 = u.pm * BM + wr * 64 + fr, col0 = u.pn * BM + wc * 32 + 8 * fq;
; #pragma unroll
;         for (int ai = 0; ai < 2; ++ai)
; #pragma unroll
;             for (int m = 0; m < 4; ++m) { const size_t ro = (size_t)(row0 + ai * HALF + m * 16) * 1024 + col0;
; #pragma unroll
;                 for (int bj = 0; bj < 2; ++bj) { const size_t o = ro + bj * HALF; const u32x4 b = *(const u32x4*)(GBr + o);
;                     f32x4 s0, s1; s0[0] = sigm(fmaxf(bf_lo(b.x), -30.f)); s0[1] = sigm(fmaxf(bf_hi(b.x), -30.f)); s0[2] = sigm(fmaxf(bf_lo(b.y), -30.f)); s0[3] = sigm(fmaxf(bf_hi(b.y), -30.f));
;                     s1[0] = sigm(fmaxf(bf_lo(b.z), -30.f)); s1[1] = sigm(fmaxf(bf_hi(b.z), -30.f)); s1[2] = sigm(fmaxf(bf_lo(b.w), -30.f)); s1[3] = sigm(fmaxf(bf_hi(b.w), -30.f));
;                     *(u32x4*)(Mx + o) = pack8(s0 * acc[ai][bj][m][0], s1 * acc[ai][bj][m][1]); } }
.LBB0_1032:
	v_lshl_add_u32 v2, s56, 8, v179
	v_ashrrev_i32_e32 v3, 31, v2
	v_lshl_or_b32 v168, s0, 8, v181
	v_lshlrev_b64 v[132:133], 10, v[2:3]
	v_ashrrev_i32_e32 v169, 31, v168
	s_cmp_lg_u32 s1, 0
	v_lshl_add_u64 v[132:133], v[132:133], 0, v[168:169]
	s_cselect_b64 s[54:55], -1, 0
	v_lshlrev_b64 v[142:143], 1, v[132:133]
	v_or_b32_e32 v172, 16, v2
	v_or_b32_e32 v170, 32, v2
	s_and_b64 vcc, exec, s[54:55]
	v_lshl_add_u64 v[132:133], s[6:7], 0, v[142:143]
	v_or_b32_e32 v140, 0x100, v142
	v_ashrrev_i32_e32 v173, 31, v172
	v_ashrrev_i32_e32 v171, 31, v170
	s_cbranch_vccz .LBB0_1040
	v_mov_b32_e32 v228, v132
	v_mov_b32_e32 v229, v133
	s_mov_b32 s98, 0x8000
	s_mov_b32 s99, 0
	global_load_dwordx4 v[184:187], v[228:229], off
	global_load_dwordx4 v[188:191], v[228:229], off offset:256
	v_lshl_add_u64 v[228:229], v[228:229], 0, s[98:99]
	global_load_dwordx4 v[192:195], v[228:229], off
	global_load_dwordx4 v[196:199], v[228:229], off offset:256
	v_lshl_add_u64 v[228:229], v[228:229], 0, s[98:99]
	global_load_dwordx4 v[200:203], v[228:229], off
	global_load_dwordx4 v[204:207], v[228:229], off offset:256
	v_lshl_add_u64 v[228:229], v[228:229], 0, s[98:99]
	global_load_dwordx4 v[208:211], v[228:229], off
	global_load_dwordx4 v[212:215], v[228:229], off offset:256
	v_lshl_add_u64 v[228:229], v[228:229], 0, s[98:99]
	v_lshl_add_u64 v[228:229], v[228:229], 0, s[98:99]
	v_lshl_add_u64 v[228:229], v[228:229], 0, s[98:99]
	v_lshl_add_u64 v[228:229], v[228:229], 0, s[98:99]
	v_lshl_add_u64 v[228:229], v[228:229], 0, s[98:99]
	global_load_dwordx4 v[216:219], v[228:229], off
	global_load_dwordx4 v[220:223], v[228:229], off offset:256
	v_lshl_add_u64 v[228:229], v[228:229], 0, s[98:99]
	global_load_dwordx4 v[224:227], v[228:229], off
	global_load_dwordx4 v[238:241], v[228:229], off offset:256
	v_lshl_add_u64 v[228:229], v[228:229], 0, s[98:99]
	global_load_dwordx4 v[242:245], v[228:229], off
	global_load_dwordx4 v[246:249], v[228:229], off offset:256
	v_lshl_add_u64 v[228:229], v[228:229], 0, s[98:99]
	global_load_dwordx4 v[252:255], v[228:229], off
	s_nop 1
	v_lshl_add_u64 v[138:139], s[16:17], 0, v[142:143]
	v_mov_b32_e32 v141, v143
	v_lshl_add_u64 v[144:145], s[6:7], 0, v[140:141]
	s_waitcnt vmcnt(14)
	v_lshlrev_b32_e32 v1, 16, v184
	v_and_b32_e32 v134, 0xffff0000, v184
	v_lshlrev_b32_e32 v146, 16, v185
	v_and_b32_e32 v135, 0xffff0000, v185
	v_lshlrev_b32_e32 v147, 16, v186
	v_and_b32_e32 v136, 0xffff0000, v186
	v_lshlrev_b32_e32 v148, 16, v187
	v_and_b32_e32 v137, 0xffff0000, v187
	global_load_dwordx4 v[184:187], v[228:229], off offset:256
	v_max_f32_e32 v1, v1, v1
	v_max_f32_e32 v134, v134, v134
	v_max_f32_e32 v146, v146, v146
	v_max_f32_e32 v135, v135, v135
	v_max_f32_e32 v147, v147, v147
	v_max_f32_e32 v136, v136, v136
	v_max_f32_e32 v148, v148, v148
	v_max_f32_e32 v137, v137, v137
	v_max_f32_e32 v1, 0xc1f00000, v1
	v_max_f32_e32 v134, 0xc1f00000, v134
	v_max_f32_e32 v146, 0xc1f00000, v146
	v_max_f32_e32 v135, 0xc1f00000, v135
	v_max_f32_e32 v147, 0xc1f00000, v147
	v_max_f32_e32 v136, 0xc1f00000, v136
	v_max_f32_e32 v148, 0xc1f00000, v148
	v_max_f32_e32 v137, 0xc1f00000, v137
	v_mul_f32_e32 v1, 0xbfb8aa3b, v1
	v_mul_f32_e32 v134, 0xbfb8aa3b, v134
	v_mul_f32_e32 v146, 0xbfb8aa3b, v146
	v_mul_f32_e32 v135, 0xbfb8aa3b, v135
	v_mul_f32_e32 v147, 0xbfb8aa3b, v147
	v_mul_f32_e32 v136, 0xbfb8aa3b, v136
	v_mul_f32_e32 v148, 0xbfb8aa3b, v148
	v_mul_f32_e32 v137, 0xbfb8aa3b, v137
	v_exp_f32_e32 v1, v1
	v_exp_f32_e32 v134, v134
	v_exp_f32_e32 v146, v146
	v_exp_f32_e32 v135, v135
	v_exp_f32_e32 v147, v147
	v_exp_f32_e32 v136, v136
	v_exp_f32_e32 v148, v148
	v_exp_f32_e32 v137, v137
	v_add_f32_e32 v1, 1.0, v1
	v_add_f32_e32 v149, 1.0, v134
	v_add_f32_e32 v146, 1.0, v146
	v_add_f32_e32 v150, 1.0, v135
	v_add_f32_e32 v147, 1.0, v147
	v_add_f32_e32 v151, 1.0, v136
	v_add_f32_e32 v148, 1.0, v148
	v_add_f32_e32 v174, 1.0, v137
	v_rcp_f32_e32 v134, v1
	v_rcp_f32_e32 v135, v149
	v_rcp_f32_e32 v136, v146
	v_rcp_f32_e32 v137, v150
	v_rcp_f32_e32 v146, v147
	v_rcp_f32_e32 v148, v148
	v_rcp_f32_e32 v149, v174
	v_rcp_f32_e32 v147, v151
	v_pk_mul_f32 v[136:137], v[130:131], v[136:137]
	v_pk_mul_f32 v[134:135], v[128:129], v[134:135]
	v_pk_mul_f32 v[148:149], v[126:127], v[148:149]
	v_pk_mul_f32 v[146:147], v[124:125], v[146:147]
	v_cvt_pk_bf16_f32 v134, v134, v135
	v_cvt_pk_bf16_f32 v135, v136, v137
	s_nop 0
	v_cvt_pk_bf16_f32 v136, v146, v147
	v_cvt_pk_bf16_f32 v137, v148, v149
	global_store_dwordx4 v[138:139], v[134:137], off
	s_nop 1
	v_lshl_add_u64 v[138:139], s[16:17], 0, v[140:141]
	v_lshlrev_b64 v[134:135], 10, v[172:173]
	v_lshl_add_u64 v[134:135], v[134:135], 0, v[168:169]
	v_lshlrev_b64 v[136:137], 1, v[134:135]
	v_lshl_add_u64 v[134:135], s[6:7], 0, v[136:137]
	s_waitcnt vmcnt(14)
; __device__ __forceinline__ float bf_lo(unsigned w) { return __uint_as_float(w << 16); }
; __device__ __forceinline__ float bf_hi(unsigned w) { return __uint_as_float(w & 0xffff0000u); }
; __device__ __forceinline__ float sigm(float x) { return __builtin_amdgcn_rcpf(1.0f + __builtin_amdgcn_exp2f(-1.4426950408889634f * x)); }
; __device__ __forceinline__ u32x4 pack8(f32x4 a, f32x4 b) { u32x4 w; w.x = cvt_pk_bf16(a[0], a[1]); w.y = cvt_pk_bf16(a[2], a[3]); w.z = cvt_pk_bf16(b[0], b[1]); w.w = cvt_pk_bf16(b[2], b[3]); return w; }
;     __device__ __forceinline__ void operator()(const f32x4 (&acc)[2][2][4][2], const Unit& u, int wr, int wc, int fr, int fq) const {
;     ...
;                 for (int bj = 0; bj < 2; ++bj) { const size_t o = ro + bj * HALF; const u32x4 b = *(const u32x4*)(GBr + o);
;                     f32x4 s0, s1; s0[0] = sigm(fmaxf(bf_lo(b.x), -30.f)); s0[1] = sigm(fmaxf(bf_hi(b.x), -30.f)); s0[2] = sigm(fmaxf(bf_lo(b.y), -30.f)); s0[3] = sigm(fmaxf(bf_hi(b.y), -30.f));
;                     s1[0] = sigm(fmaxf(bf_lo(b.z), -30.f)); s1[1] = sigm(fmaxf(bf_hi(b.z), -30.f)); s1[2] = sigm(fmaxf(bf_lo(b.w), -30.f)); s1[3] = sigm(fmaxf(bf_hi(b.w), -30.f));
;                     *(u32x4*)(Mx + o) = pack8(s0 * acc[ai][bj][m][0], s1 * acc[ai][bj][m][1]); } }
	v_lshlrev_b32_e32 v1, 16, v188
	v_and_b32_e32 v141, 0xffff0000, v188
	v_lshlrev_b32_e32 v144, 16, v189
	v_and_b32_e32 v145, 0xffff0000, v189
	v_lshlrev_b32_e32 v148, 16, v190
	v_and_b32_e32 v146, 0xffff0000, v190
	v_lshlrev_b32_e32 v149, 16, v191
	v_and_b32_e32 v147, 0xffff0000, v191
	v_max_f32_e32 v1, v1, v1
	v_max_f32_e32 v141, v141, v141
	v_max_f32_e32 v144, v144, v144
	v_max_f32_e32 v145, v145, v145
	v_max_f32_e32 v148, v148, v148
	v_max_f32_e32 v146, v146, v146
	v_max_f32_e32 v149, v149, v149
	v_max_f32_e32 v147, v147, v147
	v_max_f32_e32 v1, 0xc1f00000, v1
	v_max_f32_e32 v141, 0xc1f00000, v141
	v_max_f32_e32 v144, 0xc1f00000, v144
	v_max_f32_e32 v145, 0xc1f00000, v145
	v_max_f32_e32 v148, 0xc1f00000, v148
	v_max_f32_e32 v146, 0xc1f00000, v146
	v_max_f32_e32 v149, 0xc1f00000, v149
	v_max_f32_e32 v147, 0xc1f00000, v147
	v_mul_f32_e32 v1, 0xbfb8aa3b, v1
	v_mul_f32_e32 v141, 0xbfb8aa3b, v141
	v_mul_f32_e32 v144, 0xbfb8aa3b, v144
	v_mul_f32_e32 v145, 0xbfb8aa3b, v145
	v_mul_f32_e32 v148, 0xbfb8aa3b, v148
	v_mul_f32_e32 v146, 0xbfb8aa3b, v146
	v_mul_f32_e32 v149, 0xbfb8aa3b, v149
	v_mul_f32_e32 v147, 0xbfb8aa3b, v147
	v_exp_f32_e32 v1, v1
	v_exp_f32_e32 v141, v141
	v_exp_f32_e32 v144, v144
	v_exp_f32_e32 v145, v145
	v_exp_f32_e32 v148, v148
	v_exp_f32_e32 v146, v146
	v_exp_f32_e32 v149, v149
	v_exp_f32_e32 v147, v147
	v_add_f32_e32 v1, 1.0, v1
	v_add_f32_e32 v141, 1.0, v141
	v_add_f32_e32 v150, 1.0, v144
	v_add_f32_e32 v151, 1.0, v145
	v_add_f32_e32 v148, 1.0, v148
	v_add_f32_e32 v174, 1.0, v146
	v_add_f32_e32 v149, 1.0, v149
	v_add_f32_e32 v175, 1.0, v147
	v_rcp_f32_e32 v144, v1
	v_rcp_f32_e32 v145, v141
	v_rcp_f32_e32 v146, v150
	v_rcp_f32_e32 v147, v151
	v_rcp_f32_e32 v148, v148
	v_rcp_f32_e32 v150, v149
	v_rcp_f32_e32 v151, v175
	v_rcp_f32_e32 v149, v174
	v_pk_mul_f32 v[146:147], v[98:99], v[146:147]
	v_pk_mul_f32 v[144:145], v[96:97], v[144:145]
	v_pk_mul_f32 v[150:151], v[94:95], v[150:151]
	v_pk_mul_f32 v[148:149], v[92:93], v[148:149]
	v_cvt_pk_bf16_f32 v144, v144, v145
	v_cvt_pk_bf16_f32 v145, v146, v147
	s_nop 0
	v_cvt_pk_bf16_f32 v146, v148, v149
	v_cvt_pk_bf16_f32 v147, v150, v151
	global_store_dwordx4 v[138:139], v[144:147], off
	s_nop 1
	v_lshl_add_u64 v[134:135], s[16:17], 0, v[136:137]
	v_or_b32_e32 v136, 0x100, v136
	v_lshl_add_u64 v[138:139], s[6:7], 0, v[136:137]
	s_waitcnt vmcnt(13)
	v_lshlrev_b32_e32 v1, 16, v192
	v_and_b32_e32 v141, 0xffff0000, v192
	v_lshlrev_b32_e32 v144, 16, v193
	v_and_b32_e32 v145, 0xffff0000, v193
	v_lshlrev_b32_e32 v148, 16, v194
	v_and_b32_e32 v146, 0xffff0000, v194
	v_lshlrev_b32_e32 v149, 16, v195
	v_and_b32_e32 v147, 0xffff0000, v195
	v_max_f32_e32 v1, v1, v1
	v_max_f32_e32 v141, v141, v141
	v_max_f32_e32 v144, v144, v144
	v_max_f32_e32 v145, v145, v145
	v_max_f32_e32 v148, v148, v148
	v_max_f32_e32 v146, v146, v146
	v_max_f32_e32 v149, v149, v149
	v_max_f32_e32 v147, v147, v147
	v_max_f32_e32 v1, 0xc1f00000, v1
	v_max_f32_e32 v141, 0xc1f00000, v141
	v_max_f32_e32 v144, 0xc1f00000, v144
	v_max_f32_e32 v145, 0xc1f00000, v145
	v_max_f32_e32 v148, 0xc1f00000, v148
	v_max_f32_e32 v146, 0xc1f00000, v146
	v_max_f32_e32 v149, 0xc1f00000, v149
	v_max_f32_e32 v147, 0xc1f00000, v147
	v_mul_f32_e32 v1, 0xbfb8aa3b, v1
	v_mul_f32_e32 v141, 0xbfb8aa3b, v141
	v_mul_f32_e32 v144, 0xbfb8aa3b, v144
	v_mul_f32_e32 v145, 0xbfb8aa3b, v145
	v_mul_f32_e32 v148, 0xbfb8aa3b, v148
	v_mul_f32_e32 v146, 0xbfb8aa3b, v146
	v_mul_f32_e32 v149, 0xbfb8aa3b, v149
	v_mul_f32_e32 v147, 0xbfb8aa3b, v147
	v_exp_f32_e32 v1, v1
	v_exp_f32_e32 v141, v141
	v_exp_f32_e32 v144, v144
	v_exp_f32_e32 v145, v145
	v_exp_f32_e32 v148, v148
	v_exp_f32_e32 v146, v146
	v_exp_f32_e32 v149, v149
	v_exp_f32_e32 v147, v147
	v_add_f32_e32 v1, 1.0, v1
	v_add_f32_e32 v141, 1.0, v141
	v_add_f32_e32 v150, 1.0, v144
	v_add_f32_e32 v151, 1.0, v145
	v_add_f32_e32 v148, 1.0, v148
	v_add_f32_e32 v174, 1.0, v146
	v_add_f32_e32 v149, 1.0, v149
	v_add_f32_e32 v175, 1.0, v147
	v_rcp_f32_e32 v144, v1
	v_rcp_f32_e32 v145, v141
	v_rcp_f32_e32 v146, v150
	v_rcp_f32_e32 v147, v151
	v_rcp_f32_e32 v148, v148
	v_rcp_f32_e32 v150, v149
	v_rcp_f32_e32 v151, v175
	v_rcp_f32_e32 v149, v174
	v_pk_mul_f32 v[146:147], v[122:123], v[146:147]
	v_pk_mul_f32 v[144:145], v[120:121], v[144:145]
	v_pk_mul_f32 v[150:151], v[118:119], v[150:151]
	v_pk_mul_f32 v[148:149], v[116:117], v[148:149]
	v_cvt_pk_bf16_f32 v144, v144, v145
	v_cvt_pk_bf16_f32 v145, v146, v147
	s_nop 0
	v_cvt_pk_bf16_f32 v146, v148, v149
	v_cvt_pk_bf16_f32 v147, v150, v151
	global_store_dwordx4 v[134:135], v[144:147], off
	s_nop 1
	v_lshl_add_u64 v[150:151], s[16:17], 0, v[136:137]
	v_lshlrev_b64 v[134:135], 10, v[170:171]
	v_lshl_add_u64 v[134:135], v[134:135], 0, v[168:169]
	v_lshlrev_b64 v[134:135], 1, v[134:135]
	v_lshl_add_u64 v[148:149], s[6:7], 0, v[134:135]
	s_waitcnt vmcnt(12)
; __device__ __forceinline__ float bf_lo(unsigned w) { return __uint_as_float(w << 16); }
; __device__ __forceinline__ float bf_hi(unsigned w) { return __uint_as_float(w & 0xffff0000u); }
; __device__ __forceinline__ float sigm(float x) { return __builtin_amdgcn_rcpf(1.0f + __builtin_amdgcn_exp2f(-1.4426950408889634f * x)); }
; __device__ __forceinline__ u32x4 pack8(f32x4 a, f32x4 b) { u32x4 w; w.x = cvt_pk_bf16(a[0], a[1]); w.y = cvt_pk_bf16(a[2], a[3]); w.z = cvt_pk_bf16(b[0], b[1]); w.w = cvt_pk_bf16(b[2], b[3]); return w; }
;     __device__ __forceinline__ void operator()(const f32x4 (&acc)[2][2][4][2], const Unit& u, int wr, int wc, int fr, int fq) const {
;     ...
;                 for (int bj = 0; bj < 2; ++bj) { const size_t o = ro + bj * HALF; const u32x4 b = *(const u32x4*)(GBr + o);
;                     f32x4 s0, s1; s0[0] = sigm(fmaxf(bf_lo(b.x), -30.f)); s0[1] = sigm(fmaxf(bf_hi(b.x), -30.f)); s0[2] = sigm(fmaxf(bf_lo(b.y), -30.f)); s0[3] = sigm(fmaxf(bf_hi(b.y), -30.f));
;                     s1[0] = sigm(fmaxf(bf_lo(b.z), -30.f)); s1[1] = sigm(fmaxf(bf_hi(b.z), -30.f)); s1[2] = sigm(fmaxf(bf_lo(b.w), -30.f)); s1[3] = sigm(fmaxf(bf_hi(b.w), -30.f));
;                     *(u32x4*)(Mx + o) = pack8(s0 * acc[ai][bj][m][0], s1 * acc[ai][bj][m][1]); } }
	v_lshlrev_b32_e32 v1, 16, v196
	v_and_b32_e32 v136, 0xffff0000, v196
	v_lshlrev_b32_e32 v137, 16, v197
	v_and_b32_e32 v138, 0xffff0000, v197
	v_lshlrev_b32_e32 v139, 16, v198
	v_and_b32_e32 v141, 0xffff0000, v198
	v_lshlrev_b32_e32 v144, 16, v199
	v_and_b32_e32 v145, 0xffff0000, v199
	v_max_f32_e32 v1, v1, v1
	v_max_f32_e32 v136, v136, v136
	v_max_f32_e32 v137, v137, v137
	v_max_f32_e32 v138, v138, v138
	v_max_f32_e32 v139, v139, v139
	v_max_f32_e32 v141, v141, v141
	v_max_f32_e32 v144, v144, v144
	v_max_f32_e32 v145, v145, v145
	v_max_f32_e32 v1, 0xc1f00000, v1
	v_max_f32_e32 v136, 0xc1f00000, v136
	v_max_f32_e32 v137, 0xc1f00000, v137
	v_max_f32_e32 v138, 0xc1f00000, v138
	v_max_f32_e32 v139, 0xc1f00000, v139
	v_max_f32_e32 v141, 0xc1f00000, v141
	v_max_f32_e32 v144, 0xc1f00000, v144
	v_max_f32_e32 v145, 0xc1f00000, v145
	v_mul_f32_e32 v1, 0xbfb8aa3b, v1
	v_mul_f32_e32 v136, 0xbfb8aa3b, v136
	v_mul_f32_e32 v137, 0xbfb8aa3b, v137
	v_mul_f32_e32 v138, 0xbfb8aa3b, v138
	v_mul_f32_e32 v139, 0xbfb8aa3b, v139
	v_mul_f32_e32 v141, 0xbfb8aa3b, v141
	v_mul_f32_e32 v144, 0xbfb8aa3b, v144
	v_mul_f32_e32 v145, 0xbfb8aa3b, v145
	v_exp_f32_e32 v1, v1
	v_exp_f32_e32 v136, v136
	v_exp_f32_e32 v137, v137
	v_exp_f32_e32 v138, v138
	v_exp_f32_e32 v139, v139
	v_exp_f32_e32 v141, v141
	v_exp_f32_e32 v144, v144
	v_exp_f32_e32 v145, v145
	v_add_f32_e32 v1, 1.0, v1
	v_add_f32_e32 v146, 1.0, v136
	v_add_f32_e32 v147, 1.0, v137
	v_add_f32_e32 v174, 1.0, v138
	v_add_f32_e32 v175, 1.0, v139
	v_add_f32_e32 v141, 1.0, v141
	v_add_f32_e32 v176, 1.0, v144
	v_add_f32_e32 v145, 1.0, v145
	v_rcp_f32_e32 v136, v1
	v_rcp_f32_e32 v137, v146
	v_rcp_f32_e32 v138, v147
	v_rcp_f32_e32 v139, v174
	v_rcp_f32_e32 v144, v175
	v_rcp_f32_e32 v146, v176
	v_rcp_f32_e32 v147, v145
	v_rcp_f32_e32 v145, v141
	v_pk_mul_f32 v[138:139], v[90:91], v[138:139]
	v_pk_mul_f32 v[136:137], v[88:89], v[136:137]
	v_pk_mul_f32 v[146:147], v[86:87], v[146:147]
	v_pk_mul_f32 v[144:145], v[84:85], v[144:145]
	v_cvt_pk_bf16_f32 v136, v136, v137
	v_cvt_pk_bf16_f32 v137, v138, v139
	s_nop 0
	v_cvt_pk_bf16_f32 v138, v144, v145
	v_cvt_pk_bf16_f32 v139, v146, v147
	global_store_dwordx4 v[150:151], v[136:139], off
	s_nop 1
	v_lshl_add_u64 v[144:145], s[16:17], 0, v[134:135]
	v_or_b32_e32 v134, 0x100, v134
	v_lshl_add_u64 v[146:147], s[6:7], 0, v[134:135]
	s_waitcnt vmcnt(11)
	v_lshlrev_b32_e32 v1, 16, v200
	v_and_b32_e32 v136, 0xffff0000, v200
	v_lshlrev_b32_e32 v141, 16, v201
	v_and_b32_e32 v137, 0xffff0000, v201
	v_lshlrev_b32_e32 v148, 16, v202
	v_and_b32_e32 v138, 0xffff0000, v202
	v_lshlrev_b32_e32 v149, 16, v203
	v_and_b32_e32 v139, 0xffff0000, v203
	v_max_f32_e32 v1, v1, v1
	v_max_f32_e32 v136, v136, v136
	v_max_f32_e32 v141, v141, v141
	v_max_f32_e32 v137, v137, v137
	v_max_f32_e32 v148, v148, v148
	v_max_f32_e32 v138, v138, v138
	v_max_f32_e32 v149, v149, v149
	v_max_f32_e32 v139, v139, v139
	v_max_f32_e32 v1, 0xc1f00000, v1
	v_max_f32_e32 v136, 0xc1f00000, v136
	v_max_f32_e32 v141, 0xc1f00000, v141
	v_max_f32_e32 v137, 0xc1f00000, v137
	v_max_f32_e32 v148, 0xc1f00000, v148
	v_max_f32_e32 v138, 0xc1f00000, v138
	v_max_f32_e32 v149, 0xc1f00000, v149
	v_max_f32_e32 v139, 0xc1f00000, v139
	v_mul_f32_e32 v1, 0xbfb8aa3b, v1
	v_mul_f32_e32 v136, 0xbfb8aa3b, v136
	v_mul_f32_e32 v141, 0xbfb8aa3b, v141
	v_mul_f32_e32 v137, 0xbfb8aa3b, v137
	v_mul_f32_e32 v148, 0xbfb8aa3b, v148
	v_mul_f32_e32 v138, 0xbfb8aa3b, v138
	v_mul_f32_e32 v149, 0xbfb8aa3b, v149
	v_mul_f32_e32 v139, 0xbfb8aa3b, v139
	v_exp_f32_e32 v1, v1
	v_exp_f32_e32 v136, v136
	v_exp_f32_e32 v141, v141
	v_exp_f32_e32 v137, v137
	v_exp_f32_e32 v148, v148
	v_exp_f32_e32 v138, v138
	v_exp_f32_e32 v149, v149
	v_exp_f32_e32 v139, v139
	v_add_f32_e32 v1, 1.0, v1
	v_add_f32_e32 v150, 1.0, v136
	v_add_f32_e32 v141, 1.0, v141
	v_add_f32_e32 v151, 1.0, v137
	v_add_f32_e32 v148, 1.0, v148
	v_add_f32_e32 v174, 1.0, v138
	v_add_f32_e32 v149, 1.0, v149
	v_add_f32_e32 v175, 1.0, v139
	v_rcp_f32_e32 v136, v1
	v_rcp_f32_e32 v137, v150
	v_rcp_f32_e32 v138, v141
	v_rcp_f32_e32 v139, v151
	v_rcp_f32_e32 v148, v148
	v_rcp_f32_e32 v150, v149
	v_rcp_f32_e32 v151, v175
	v_rcp_f32_e32 v149, v174
	v_pk_mul_f32 v[138:139], v[114:115], v[138:139]
	v_pk_mul_f32 v[136:137], v[112:113], v[136:137]
	v_pk_mul_f32 v[150:151], v[110:111], v[150:151]
	v_pk_mul_f32 v[148:149], v[108:109], v[148:149]
	v_cvt_pk_bf16_f32 v136, v136, v137
	v_cvt_pk_bf16_f32 v137, v138, v139
	s_nop 0
	v_cvt_pk_bf16_f32 v138, v148, v149
	v_cvt_pk_bf16_f32 v139, v150, v151
	global_store_dwordx4 v[144:145], v[136:139], off
	s_nop 1
	v_or_b32_e32 v144, 48, v2
	v_ashrrev_i32_e32 v145, 31, v144
	v_lshlrev_b64 v[144:145], 10, v[144:145]
	v_lshl_add_u64 v[144:145], v[144:145], 0, v[168:169]
	v_lshl_add_u64 v[146:147], s[16:17], 0, v[134:135]
	v_lshlrev_b64 v[134:135], 1, v[144:145]
	v_lshl_add_u64 v[144:145], s[6:7], 0, v[134:135]
	s_waitcnt vmcnt(10)
; __device__ __forceinline__ float bf_lo(unsigned w) { return __uint_as_float(w << 16); }
; __device__ __forceinline__ float bf_hi(unsigned w) { return __uint_as_float(w & 0xffff0000u); }
; __device__ __forceinline__ float sigm(float x) { return __builtin_amdgcn_rcpf(1.0f + __builtin_amdgcn_exp2f(-1.4426950408889634f * x)); }
; __device__ __forceinline__ u32x4 pack8(f32x4 a, f32x4 b) { u32x4 w; w.x = cvt_pk_bf16(a[0], a[1]); w.y = cvt_pk_bf16(a[2], a[3]); w.z = cvt_pk_bf16(b[0], b[1]); w.w = cvt_pk_bf16(b[2], b[3]); return w; }
;     __device__ __forceinline__ void operator()(const f32x4 (&acc)[2][2][4][2], const Unit& u, int wr, int wc, int fr, int fq) const {
;     ...
;                 for (int bj = 0; bj < 2; ++bj) { const size_t o = ro + bj * HALF; const u32x4 b = *(const u32x4*)(GBr + o);
;                     f32x4 s0, s1; s0[0] = sigm(fmaxf(bf_lo(b.x), -30.f)); s0[1] = sigm(fmaxf(bf_hi(b.x), -30.f)); s0[2] = sigm(fmaxf(bf_lo(b.y), -30.f)); s0[3] = sigm(fmaxf(bf_hi(b.y), -30.f));
;                     s1[0] = sigm(fmaxf(bf_lo(b.z), -30.f)); s1[1] = sigm(fmaxf(bf_hi(b.z), -30.f)); s1[2] = sigm(fmaxf(bf_lo(b.w), -30.f)); s1[3] = sigm(fmaxf(bf_hi(b.w), -30.f));
;                     *(u32x4*)(Mx + o) = pack8(s0 * acc[ai][bj][m][0], s1 * acc[ai][bj][m][1]); } }
	v_lshlrev_b32_e32 v1, 16, v204
	v_and_b32_e32 v136, 0xffff0000, v204
	v_lshlrev_b32_e32 v141, 16, v205
	v_and_b32_e32 v137, 0xffff0000, v205
	v_lshlrev_b32_e32 v148, 16, v206
	v_and_b32_e32 v138, 0xffff0000, v206
	v_lshlrev_b32_e32 v149, 16, v207
	v_and_b32_e32 v139, 0xffff0000, v207
	v_max_f32_e32 v1, v1, v1
	v_max_f32_e32 v136, v136, v136
	v_max_f32_e32 v141, v141, v141
	v_max_f32_e32 v137, v137, v137
	v_max_f32_e32 v148, v148, v148
	v_max_f32_e32 v138, v138, v138
	v_max_f32_e32 v149, v149, v149
	v_max_f32_e32 v139, v139, v139
	v_max_f32_e32 v1, 0xc1f00000, v1
	v_max_f32_e32 v136, 0xc1f00000, v136
	v_max_f32_e32 v141, 0xc1f00000, v141
	v_max_f32_e32 v137, 0xc1f00000, v137
	v_max_f32_e32 v148, 0xc1f00000, v148
	v_max_f32_e32 v138, 0xc1f00000, v138
	v_max_f32_e32 v149, 0xc1f00000, v149
	v_max_f32_e32 v139, 0xc1f00000, v139
	v_mul_f32_e32 v1, 0xbfb8aa3b, v1
	v_mul_f32_e32 v136, 0xbfb8aa3b, v136
	v_mul_f32_e32 v141, 0xbfb8aa3b, v141
	v_mul_f32_e32 v137, 0xbfb8aa3b, v137
	v_mul_f32_e32 v148, 0xbfb8aa3b, v148
	v_mul_f32_e32 v138, 0xbfb8aa3b, v138
	v_mul_f32_e32 v149, 0xbfb8aa3b, v149
	v_mul_f32_e32 v139, 0xbfb8aa3b, v139
	v_exp_f32_e32 v1, v1
	v_exp_f32_e32 v136, v136
	v_exp_f32_e32 v141, v141
	v_exp_f32_e32 v137, v137
	v_exp_f32_e32 v148, v148
	v_exp_f32_e32 v138, v138
	v_exp_f32_e32 v149, v149
	v_exp_f32_e32 v139, v139
	v_add_f32_e32 v1, 1.0, v1
	v_add_f32_e32 v150, 1.0, v136
	v_add_f32_e32 v141, 1.0, v141
	v_add_f32_e32 v151, 1.0, v137
	v_add_f32_e32 v148, 1.0, v148
	v_add_f32_e32 v174, 1.0, v138
	v_add_f32_e32 v149, 1.0, v149
	v_add_f32_e32 v175, 1.0, v139
	v_rcp_f32_e32 v136, v1
	v_rcp_f32_e32 v137, v150
	v_rcp_f32_e32 v138, v141
	v_rcp_f32_e32 v139, v151
	v_rcp_f32_e32 v148, v148
	v_rcp_f32_e32 v150, v149
	v_rcp_f32_e32 v151, v175
	v_rcp_f32_e32 v149, v174
	v_pk_mul_f32 v[138:139], v[82:83], v[138:139]
	v_pk_mul_f32 v[136:137], v[80:81], v[136:137]
	v_pk_mul_f32 v[150:151], v[78:79], v[150:151]
	v_pk_mul_f32 v[148:149], v[76:77], v[148:149]
	v_cvt_pk_bf16_f32 v136, v136, v137
	v_cvt_pk_bf16_f32 v137, v138, v139
	s_nop 0
	v_cvt_pk_bf16_f32 v138, v148, v149
	v_cvt_pk_bf16_f32 v139, v150, v151
	global_store_dwordx4 v[146:147], v[136:139], off
	s_nop 1
	v_lshl_add_u64 v[144:145], s[16:17], 0, v[134:135]
	v_or_b32_e32 v134, 0x100, v134
	v_lshl_add_u64 v[146:147], s[6:7], 0, v[134:135]
	s_waitcnt vmcnt(9)
	v_lshlrev_b32_e32 v1, 16, v208
	v_and_b32_e32 v136, 0xffff0000, v208
	v_lshlrev_b32_e32 v141, 16, v209
	v_and_b32_e32 v137, 0xffff0000, v209
	v_lshlrev_b32_e32 v148, 16, v210
	v_and_b32_e32 v138, 0xffff0000, v210
	v_lshlrev_b32_e32 v149, 16, v211
	v_and_b32_e32 v139, 0xffff0000, v211
	v_max_f32_e32 v1, v1, v1
	v_max_f32_e32 v136, v136, v136
	v_max_f32_e32 v141, v141, v141
	v_max_f32_e32 v137, v137, v137
	v_max_f32_e32 v148, v148, v148
	v_max_f32_e32 v138, v138, v138
	v_max_f32_e32 v149, v149, v149
	v_max_f32_e32 v139, v139, v139
	v_max_f32_e32 v1, 0xc1f00000, v1
	v_max_f32_e32 v136, 0xc1f00000, v136
	v_max_f32_e32 v141, 0xc1f00000, v141
	v_max_f32_e32 v137, 0xc1f00000, v137
	v_max_f32_e32 v148, 0xc1f00000, v148
	v_max_f32_e32 v138, 0xc1f00000, v138
	v_max_f32_e32 v149, 0xc1f00000, v149
	v_max_f32_e32 v139, 0xc1f00000, v139
	v_mul_f32_e32 v1, 0xbfb8aa3b, v1
	v_mul_f32_e32 v136, 0xbfb8aa3b, v136
	v_mul_f32_e32 v141, 0xbfb8aa3b, v141
	v_mul_f32_e32 v137, 0xbfb8aa3b, v137
	v_mul_f32_e32 v148, 0xbfb8aa3b, v148
	v_mul_f32_e32 v138, 0xbfb8aa3b, v138
	v_mul_f32_e32 v149, 0xbfb8aa3b, v149
	v_mul_f32_e32 v139, 0xbfb8aa3b, v139
	v_exp_f32_e32 v1, v1
	v_exp_f32_e32 v136, v136
	v_exp_f32_e32 v141, v141
	v_exp_f32_e32 v137, v137
	v_exp_f32_e32 v148, v148
	v_exp_f32_e32 v138, v138
	v_exp_f32_e32 v149, v149
	v_exp_f32_e32 v139, v139
	v_add_f32_e32 v1, 1.0, v1
	v_add_f32_e32 v150, 1.0, v136
	v_add_f32_e32 v141, 1.0, v141
	v_add_f32_e32 v151, 1.0, v137
	v_add_f32_e32 v148, 1.0, v148
	v_add_f32_e32 v174, 1.0, v138
	v_add_f32_e32 v149, 1.0, v149
	v_add_f32_e32 v175, 1.0, v139
	v_rcp_f32_e32 v136, v1
	v_rcp_f32_e32 v137, v150
	v_rcp_f32_e32 v138, v141
	v_rcp_f32_e32 v139, v151
	v_rcp_f32_e32 v148, v148
	v_rcp_f32_e32 v150, v149
	v_rcp_f32_e32 v151, v175
	v_rcp_f32_e32 v149, v174
	v_pk_mul_f32 v[138:139], v[106:107], v[138:139]
	v_pk_mul_f32 v[136:137], v[104:105], v[136:137]
	v_pk_mul_f32 v[150:151], v[102:103], v[150:151]
	v_pk_mul_f32 v[148:149], v[100:101], v[148:149]
	v_cvt_pk_bf16_f32 v136, v136, v137
	v_cvt_pk_bf16_f32 v137, v138, v139
	s_nop 0
	v_cvt_pk_bf16_f32 v138, v148, v149
	v_cvt_pk_bf16_f32 v139, v150, v151
	global_store_dwordx4 v[144:145], v[136:139], off
	s_nop 1
	v_lshl_add_u64 v[148:149], s[16:17], 0, v[134:135]
	v_lshl_add_u64 v[144:145], v[142:143], 0, s[18:19]
	v_lshl_add_u64 v[146:147], s[6:7], 0, v[144:145]
	v_lshl_add_u64 v[144:145], s[16:17], 0, v[144:145]
	s_waitcnt vmcnt(8)
; __device__ __forceinline__ float bf_lo(unsigned w) { return __uint_as_float(w << 16); }
; __device__ __forceinline__ float bf_hi(unsigned w) { return __uint_as_float(w & 0xffff0000u); }
; __device__ __forceinline__ float sigm(float x) { return __builtin_amdgcn_rcpf(1.0f + __builtin_amdgcn_exp2f(-1.4426950408889634f * x)); }
; __device__ __forceinline__ u32x4 pack8(f32x4 a, f32x4 b) { u32x4 w; w.x = cvt_pk_bf16(a[0], a[1]); w.y = cvt_pk_bf16(a[2], a[3]); w.z = cvt_pk_bf16(b[0], b[1]); w.w = cvt_pk_bf16(b[2], b[3]); return w; }
;     __device__ __forceinline__ void operator()(const f32x4 (&acc)[2][2][4][2], const Unit& u, int wr, int wc, int fr, int fq) const {
;     ...
;                 for (int bj = 0; bj < 2; ++bj) { const size_t o = ro + bj * HALF; const u32x4 b = *(const u32x4*)(GBr + o);
;                     f32x4 s0, s1; s0[0] = sigm(fmaxf(bf_lo(b.x), -30.f)); s0[1] = sigm(fmaxf(bf_hi(b.x), -30.f)); s0[2] = sigm(fmaxf(bf_lo(b.y), -30.f)); s0[3] = sigm(fmaxf(bf_hi(b.y), -30.f));
;                     s1[0] = sigm(fmaxf(bf_lo(b.z), -30.f)); s1[1] = sigm(fmaxf(bf_hi(b.z), -30.f)); s1[2] = sigm(fmaxf(bf_lo(b.w), -30.f)); s1[3] = sigm(fmaxf(bf_hi(b.w), -30.f));
;                     *(u32x4*)(Mx + o) = pack8(s0 * acc[ai][bj][m][0], s1 * acc[ai][bj][m][1]); } }
	v_lshlrev_b32_e32 v1, 16, v212
	v_and_b32_e32 v134, 0xffff0000, v212
	v_lshlrev_b32_e32 v135, 16, v213
	v_and_b32_e32 v136, 0xffff0000, v213
	v_lshlrev_b32_e32 v137, 16, v214
	v_and_b32_e32 v138, 0xffff0000, v214
	v_lshlrev_b32_e32 v141, 16, v215
	v_and_b32_e32 v139, 0xffff0000, v215
	v_max_f32_e32 v1, v1, v1
	v_max_f32_e32 v134, v134, v134
	v_max_f32_e32 v135, v135, v135
	v_max_f32_e32 v136, v136, v136
	v_max_f32_e32 v137, v137, v137
	v_max_f32_e32 v138, v138, v138
	v_max_f32_e32 v141, v141, v141
	v_max_f32_e32 v139, v139, v139
	v_max_f32_e32 v1, 0xc1f00000, v1
	v_max_f32_e32 v134, 0xc1f00000, v134
	v_max_f32_e32 v135, 0xc1f00000, v135
	v_max_f32_e32 v136, 0xc1f00000, v136
	v_max_f32_e32 v137, 0xc1f00000, v137
	v_max_f32_e32 v138, 0xc1f00000, v138
	v_max_f32_e32 v141, 0xc1f00000, v141
	v_max_f32_e32 v139, 0xc1f00000, v139
	v_mul_f32_e32 v1, 0xbfb8aa3b, v1
	v_mul_f32_e32 v134, 0xbfb8aa3b, v134
	v_mul_f32_e32 v135, 0xbfb8aa3b, v135
	v_mul_f32_e32 v136, 0xbfb8aa3b, v136
	v_mul_f32_e32 v137, 0xbfb8aa3b, v137
	v_mul_f32_e32 v138, 0xbfb8aa3b, v138
	v_mul_f32_e32 v141, 0xbfb8aa3b, v141
	v_mul_f32_e32 v139, 0xbfb8aa3b, v139
	v_exp_f32_e32 v1, v1
	v_exp_f32_e32 v134, v134
	v_exp_f32_e32 v135, v135
	v_exp_f32_e32 v136, v136
	v_exp_f32_e32 v137, v137
	v_exp_f32_e32 v138, v138
	v_exp_f32_e32 v141, v141
	v_exp_f32_e32 v139, v139
	v_add_f32_e32 v1, 1.0, v1
	v_add_f32_e32 v150, 1.0, v134
	v_add_f32_e32 v151, 1.0, v135
	v_add_f32_e32 v174, 1.0, v136
	v_add_f32_e32 v175, 1.0, v137
	v_add_f32_e32 v176, 1.0, v138
	v_add_f32_e32 v141, 1.0, v141
	v_add_f32_e32 v139, 1.0, v139
	v_rcp_f32_e32 v134, v1
	v_rcp_f32_e32 v135, v150
	v_rcp_f32_e32 v136, v151
	v_rcp_f32_e32 v137, v174
	v_rcp_f32_e32 v138, v175
	v_rcp_f32_e32 v150, v141
	v_rcp_f32_e32 v151, v139
	v_rcp_f32_e32 v139, v176
	v_pk_mul_f32 v[136:137], v[74:75], v[136:137]
	v_pk_mul_f32 v[134:135], v[72:73], v[134:135]
	v_pk_mul_f32 v[150:151], v[70:71], v[150:151]
	v_pk_mul_f32 v[138:139], v[68:69], v[138:139]
	v_cvt_pk_bf16_f32 v134, v134, v135
	v_cvt_pk_bf16_f32 v135, v136, v137
	s_nop 0
	v_cvt_pk_bf16_f32 v136, v138, v139
	v_cvt_pk_bf16_f32 v137, v150, v151
	global_store_dwordx4 v[148:149], v[134:137], off
	s_nop 1
	v_lshl_add_u64 v[138:139], v[142:143], 0, s[30:31]
	v_lshl_add_u64 v[146:147], s[6:7], 0, v[138:139]
	v_lshl_add_u64 v[138:139], s[16:17], 0, v[138:139]
	s_waitcnt vmcnt(7)
	v_lshlrev_b32_e32 v1, 16, v216
	v_and_b32_e32 v134, 0xffff0000, v216
	v_lshlrev_b32_e32 v141, 16, v217
	v_and_b32_e32 v135, 0xffff0000, v217
	v_lshlrev_b32_e32 v148, 16, v218
	v_and_b32_e32 v136, 0xffff0000, v218
	v_lshlrev_b32_e32 v149, 16, v219
	v_and_b32_e32 v137, 0xffff0000, v219
	v_max_f32_e32 v1, v1, v1
	v_max_f32_e32 v134, v134, v134
	v_max_f32_e32 v141, v141, v141
	v_max_f32_e32 v135, v135, v135
	v_max_f32_e32 v148, v148, v148
	v_max_f32_e32 v136, v136, v136
	v_max_f32_e32 v149, v149, v149
	v_max_f32_e32 v137, v137, v137
	v_max_f32_e32 v1, 0xc1f00000, v1
	v_max_f32_e32 v134, 0xc1f00000, v134
	v_max_f32_e32 v141, 0xc1f00000, v141
	v_max_f32_e32 v135, 0xc1f00000, v135
	v_max_f32_e32 v148, 0xc1f00000, v148
	v_max_f32_e32 v136, 0xc1f00000, v136
	v_max_f32_e32 v149, 0xc1f00000, v149
	v_max_f32_e32 v137, 0xc1f00000, v137
	v_mul_f32_e32 v1, 0xbfb8aa3b, v1
	v_mul_f32_e32 v134, 0xbfb8aa3b, v134
	v_mul_f32_e32 v141, 0xbfb8aa3b, v141
	v_mul_f32_e32 v135, 0xbfb8aa3b, v135
	v_mul_f32_e32 v148, 0xbfb8aa3b, v148
	v_mul_f32_e32 v136, 0xbfb8aa3b, v136
	v_mul_f32_e32 v149, 0xbfb8aa3b, v149
	v_mul_f32_e32 v137, 0xbfb8aa3b, v137
	v_exp_f32_e32 v1, v1
	v_exp_f32_e32 v134, v134
	v_exp_f32_e32 v141, v141
	v_exp_f32_e32 v135, v135
	v_exp_f32_e32 v148, v148
	v_exp_f32_e32 v136, v136
	v_exp_f32_e32 v149, v149
	v_exp_f32_e32 v137, v137
	v_add_f32_e32 v1, 1.0, v1
	v_add_f32_e32 v150, 1.0, v134
	v_add_f32_e32 v141, 1.0, v141
	v_add_f32_e32 v151, 1.0, v135
	v_add_f32_e32 v148, 1.0, v148
	v_add_f32_e32 v174, 1.0, v136
	v_add_f32_e32 v149, 1.0, v149
	v_add_f32_e32 v175, 1.0, v137
	v_rcp_f32_e32 v134, v1
	v_rcp_f32_e32 v135, v150
	v_rcp_f32_e32 v136, v141
	v_rcp_f32_e32 v137, v151
	v_rcp_f32_e32 v148, v148
	v_rcp_f32_e32 v150, v149
	v_rcp_f32_e32 v151, v175
	v_rcp_f32_e32 v149, v174
	v_pk_mul_f32 v[136:137], v[66:67], v[136:137]
	v_pk_mul_f32 v[134:135], v[64:65], v[134:135]
	v_pk_mul_f32 v[150:151], v[62:63], v[150:151]
	v_pk_mul_f32 v[148:149], v[60:61], v[148:149]
	v_cvt_pk_bf16_f32 v134, v134, v135
	v_cvt_pk_bf16_f32 v135, v136, v137
	s_nop 0
	v_cvt_pk_bf16_f32 v136, v148, v149
	v_cvt_pk_bf16_f32 v137, v150, v151
	global_store_dwordx4 v[144:145], v[134:137], off
	s_nop 1
	v_lshl_add_u64 v[144:145], v[142:143], 0, s[34:35]
	v_lshl_add_u64 v[146:147], s[6:7], 0, v[144:145]
	v_lshl_add_u64 v[144:145], s[16:17], 0, v[144:145]
	s_waitcnt vmcnt(6)
; __device__ __forceinline__ float bf_lo(unsigned w) { return __uint_as_float(w << 16); }
; __device__ __forceinline__ float bf_hi(unsigned w) { return __uint_as_float(w & 0xffff0000u); }
; __device__ __forceinline__ float sigm(float x) { return __builtin_amdgcn_rcpf(1.0f + __builtin_amdgcn_exp2f(-1.4426950408889634f * x)); }
; __device__ __forceinline__ u32x4 pack8(f32x4 a, f32x4 b) { u32x4 w; w.x = cvt_pk_bf16(a[0], a[1]); w.y = cvt_pk_bf16(a[2], a[3]); w.z = cvt_pk_bf16(b[0], b[1]); w.w = cvt_pk_bf16(b[2], b[3]); return w; }
;     __device__ __forceinline__ void operator()(const f32x4 (&acc)[2][2][4][2], const Unit& u, int wr, int wc, int fr, int fq) const {
;     ...
;                 for (int bj = 0; bj < 2; ++bj) { const size_t o = ro + bj * HALF; const u32x4 b = *(const u32x4*)(GBr + o);
;                     f32x4 s0, s1; s0[0] = sigm(fmaxf(bf_lo(b.x), -30.f)); s0[1] = sigm(fmaxf(bf_hi(b.x), -30.f)); s0[2] = sigm(fmaxf(bf_lo(b.y), -30.f)); s0[3] = sigm(fmaxf(bf_hi(b.y), -30.f));
;                     s1[0] = sigm(fmaxf(bf_lo(b.z), -30.f)); s1[1] = sigm(fmaxf(bf_hi(b.z), -30.f)); s1[2] = sigm(fmaxf(bf_lo(b.w), -30.f)); s1[3] = sigm(fmaxf(bf_hi(b.w), -30.f));
;                     *(u32x4*)(Mx + o) = pack8(s0 * acc[ai][bj][m][0], s1 * acc[ai][bj][m][1]); } }
	v_lshlrev_b32_e32 v1, 16, v220
	v_and_b32_e32 v134, 0xffff0000, v220
	v_lshlrev_b32_e32 v141, 16, v221
	v_and_b32_e32 v135, 0xffff0000, v221
	v_lshlrev_b32_e32 v148, 16, v222
	v_and_b32_e32 v136, 0xffff0000, v222
	v_lshlrev_b32_e32 v149, 16, v223
	v_and_b32_e32 v137, 0xffff0000, v223
	v_max_f32_e32 v1, v1, v1
	v_max_f32_e32 v134, v134, v134
	v_max_f32_e32 v141, v141, v141
	v_max_f32_e32 v135, v135, v135
	v_max_f32_e32 v148, v148, v148
	v_max_f32_e32 v136, v136, v136
	v_max_f32_e32 v149, v149, v149
	v_max_f32_e32 v137, v137, v137
	v_max_f32_e32 v1, 0xc1f00000, v1
	v_max_f32_e32 v134, 0xc1f00000, v134
	v_max_f32_e32 v141, 0xc1f00000, v141
	v_max_f32_e32 v135, 0xc1f00000, v135
	v_max_f32_e32 v148, 0xc1f00000, v148
	v_max_f32_e32 v136, 0xc1f00000, v136
	v_max_f32_e32 v149, 0xc1f00000, v149
	v_max_f32_e32 v137, 0xc1f00000, v137
	v_mul_f32_e32 v1, 0xbfb8aa3b, v1
	v_mul_f32_e32 v134, 0xbfb8aa3b, v134
	v_mul_f32_e32 v141, 0xbfb8aa3b, v141
	v_mul_f32_e32 v135, 0xbfb8aa3b, v135
	v_mul_f32_e32 v148, 0xbfb8aa3b, v148
	v_mul_f32_e32 v136, 0xbfb8aa3b, v136
	v_mul_f32_e32 v149, 0xbfb8aa3b, v149
	v_mul_f32_e32 v137, 0xbfb8aa3b, v137
	v_exp_f32_e32 v1, v1
	v_exp_f32_e32 v134, v134
	v_exp_f32_e32 v141, v141
	v_exp_f32_e32 v135, v135
	v_exp_f32_e32 v148, v148
	v_exp_f32_e32 v136, v136
	v_exp_f32_e32 v149, v149
	v_exp_f32_e32 v137, v137
	v_add_f32_e32 v1, 1.0, v1
	v_add_f32_e32 v150, 1.0, v134
	v_add_f32_e32 v141, 1.0, v141
	v_add_f32_e32 v151, 1.0, v135
	v_add_f32_e32 v148, 1.0, v148
	v_add_f32_e32 v174, 1.0, v136
	v_add_f32_e32 v149, 1.0, v149
	v_add_f32_e32 v175, 1.0, v137
	v_rcp_f32_e32 v134, v1
	v_rcp_f32_e32 v135, v150
	v_rcp_f32_e32 v136, v141
	v_rcp_f32_e32 v137, v151
	v_rcp_f32_e32 v148, v148
	v_rcp_f32_e32 v150, v149
	v_rcp_f32_e32 v151, v175
	v_rcp_f32_e32 v149, v174
	v_pk_mul_f32 v[136:137], v[34:35], v[136:137]
	v_pk_mul_f32 v[134:135], v[32:33], v[134:135]
	v_pk_mul_f32 v[150:151], v[30:31], v[150:151]
	v_pk_mul_f32 v[148:149], v[28:29], v[148:149]
	v_cvt_pk_bf16_f32 v134, v134, v135
	v_cvt_pk_bf16_f32 v135, v136, v137
	s_nop 0
	v_cvt_pk_bf16_f32 v136, v148, v149
	v_cvt_pk_bf16_f32 v137, v150, v151
	global_store_dwordx4 v[138:139], v[134:137], off
	s_nop 1
	v_lshl_add_u64 v[138:139], v[142:143], 0, s[36:37]
	v_lshl_add_u64 v[146:147], s[6:7], 0, v[138:139]
	v_lshl_add_u64 v[138:139], s[16:17], 0, v[138:139]
	s_waitcnt vmcnt(5)
	v_lshlrev_b32_e32 v1, 16, v224
	v_and_b32_e32 v134, 0xffff0000, v224
	v_lshlrev_b32_e32 v141, 16, v225
	v_and_b32_e32 v135, 0xffff0000, v225
	v_lshlrev_b32_e32 v148, 16, v226
	v_and_b32_e32 v136, 0xffff0000, v226
	v_lshlrev_b32_e32 v149, 16, v227
	v_and_b32_e32 v137, 0xffff0000, v227
	v_max_f32_e32 v1, v1, v1
	v_max_f32_e32 v134, v134, v134
	v_max_f32_e32 v141, v141, v141
	v_max_f32_e32 v135, v135, v135
	v_max_f32_e32 v148, v148, v148
	v_max_f32_e32 v136, v136, v136
	v_max_f32_e32 v149, v149, v149
	v_max_f32_e32 v137, v137, v137
	v_max_f32_e32 v1, 0xc1f00000, v1
	v_max_f32_e32 v134, 0xc1f00000, v134
	v_max_f32_e32 v141, 0xc1f00000, v141
	v_max_f32_e32 v135, 0xc1f00000, v135
	v_max_f32_e32 v148, 0xc1f00000, v148
	v_max_f32_e32 v136, 0xc1f00000, v136
	v_max_f32_e32 v149, 0xc1f00000, v149
	v_max_f32_e32 v137, 0xc1f00000, v137
	v_mul_f32_e32 v1, 0xbfb8aa3b, v1
	v_mul_f32_e32 v134, 0xbfb8aa3b, v134
	v_mul_f32_e32 v141, 0xbfb8aa3b, v141
	v_mul_f32_e32 v135, 0xbfb8aa3b, v135
	v_mul_f32_e32 v148, 0xbfb8aa3b, v148
	v_mul_f32_e32 v136, 0xbfb8aa3b, v136
	v_mul_f32_e32 v149, 0xbfb8aa3b, v149
	v_mul_f32_e32 v137, 0xbfb8aa3b, v137
	v_exp_f32_e32 v1, v1
	v_exp_f32_e32 v134, v134
	v_exp_f32_e32 v141, v141
	v_exp_f32_e32 v135, v135
	v_exp_f32_e32 v148, v148
	v_exp_f32_e32 v136, v136
	v_exp_f32_e32 v149, v149
	v_exp_f32_e32 v137, v137
	v_add_f32_e32 v1, 1.0, v1
	v_add_f32_e32 v150, 1.0, v134
	v_add_f32_e32 v141, 1.0, v141
	v_add_f32_e32 v151, 1.0, v135
	v_add_f32_e32 v148, 1.0, v148
	v_add_f32_e32 v174, 1.0, v136
	v_add_f32_e32 v149, 1.0, v149
	v_add_f32_e32 v175, 1.0, v137
	v_rcp_f32_e32 v134, v1
	v_rcp_f32_e32 v135, v150
	v_rcp_f32_e32 v136, v141
	v_rcp_f32_e32 v137, v151
	v_rcp_f32_e32 v148, v148
	v_rcp_f32_e32 v150, v149
	v_rcp_f32_e32 v151, v175
	v_rcp_f32_e32 v149, v174
	v_pk_mul_f32 v[136:137], v[58:59], v[136:137]
	v_pk_mul_f32 v[134:135], v[56:57], v[134:135]
	v_pk_mul_f32 v[150:151], v[54:55], v[150:151]
	v_pk_mul_f32 v[148:149], v[52:53], v[148:149]
	v_cvt_pk_bf16_f32 v134, v134, v135
	v_cvt_pk_bf16_f32 v135, v136, v137
	s_nop 0
	v_cvt_pk_bf16_f32 v136, v148, v149
	v_cvt_pk_bf16_f32 v137, v150, v151
	global_store_dwordx4 v[144:145], v[134:137], off
	s_nop 1
	v_lshl_add_u64 v[144:145], v[142:143], 0, s[38:39]
	v_lshl_add_u64 v[146:147], s[6:7], 0, v[144:145]
	v_lshl_add_u64 v[144:145], s[16:17], 0, v[144:145]
	s_waitcnt vmcnt(4)
; __device__ __forceinline__ float bf_lo(unsigned w) { return __uint_as_float(w << 16); }
; __device__ __forceinline__ float bf_hi(unsigned w) { return __uint_as_float(w & 0xffff0000u); }
; __device__ __forceinline__ float sigm(float x) { return __builtin_amdgcn_rcpf(1.0f + __builtin_amdgcn_exp2f(-1.4426950408889634f * x)); }
; __device__ __forceinline__ u32x4 pack8(f32x4 a, f32x4 b) { u32x4 w; w.x = cvt_pk_bf16(a[0], a[1]); w.y = cvt_pk_bf16(a[2], a[3]); w.z = cvt_pk_bf16(b[0], b[1]); w.w = cvt_pk_bf16(b[2], b[3]); return w; }
;     __device__ __forceinline__ void operator()(const f32x4 (&acc)[2][2][4][2], const Unit& u, int wr, int wc, int fr, int fq) const {
;     ...
;                 for (int bj = 0; bj < 2; ++bj) { const size_t o = ro + bj * HALF; const u32x4 b = *(const u32x4*)(GBr + o);
;                     f32x4 s0, s1; s0[0] = sigm(fmaxf(bf_lo(b.x), -30.f)); s0[1] = sigm(fmaxf(bf_hi(b.x), -30.f)); s0[2] = sigm(fmaxf(bf_lo(b.y), -30.f)); s0[3] = sigm(fmaxf(bf_hi(b.y), -30.f));
;                     s1[0] = sigm(fmaxf(bf_lo(b.z), -30.f)); s1[1] = sigm(fmaxf(bf_hi(b.z), -30.f)); s1[2] = sigm(fmaxf(bf_lo(b.w), -30.f)); s1[3] = sigm(fmaxf(bf_hi(b.w), -30.f));
;                     *(u32x4*)(Mx + o) = pack8(s0 * acc[ai][bj][m][0], s1 * acc[ai][bj][m][1]); } }
	v_lshlrev_b32_e32 v1, 16, v238
	v_and_b32_e32 v134, 0xffff0000, v238
	v_lshlrev_b32_e32 v141, 16, v239
	v_and_b32_e32 v135, 0xffff0000, v239
	v_lshlrev_b32_e32 v148, 16, v240
	v_and_b32_e32 v136, 0xffff0000, v240
	v_lshlrev_b32_e32 v149, 16, v241
	v_and_b32_e32 v137, 0xffff0000, v241
	v_max_f32_e32 v1, v1, v1
	v_max_f32_e32 v134, v134, v134
	v_max_f32_e32 v141, v141, v141
	v_max_f32_e32 v135, v135, v135
	v_max_f32_e32 v148, v148, v148
	v_max_f32_e32 v136, v136, v136
	v_max_f32_e32 v149, v149, v149
	v_max_f32_e32 v137, v137, v137
	v_max_f32_e32 v1, 0xc1f00000, v1
	v_max_f32_e32 v134, 0xc1f00000, v134
	v_max_f32_e32 v141, 0xc1f00000, v141
	v_max_f32_e32 v135, 0xc1f00000, v135
	v_max_f32_e32 v148, 0xc1f00000, v148
	v_max_f32_e32 v136, 0xc1f00000, v136
	v_max_f32_e32 v149, 0xc1f00000, v149
	v_max_f32_e32 v137, 0xc1f00000, v137
	v_mul_f32_e32 v1, 0xbfb8aa3b, v1
	v_mul_f32_e32 v134, 0xbfb8aa3b, v134
	v_mul_f32_e32 v141, 0xbfb8aa3b, v141
	v_mul_f32_e32 v135, 0xbfb8aa3b, v135
	v_mul_f32_e32 v148, 0xbfb8aa3b, v148
	v_mul_f32_e32 v136, 0xbfb8aa3b, v136
	v_mul_f32_e32 v149, 0xbfb8aa3b, v149
	v_mul_f32_e32 v137, 0xbfb8aa3b, v137
	v_exp_f32_e32 v1, v1
	v_exp_f32_e32 v134, v134
	v_exp_f32_e32 v141, v141
	v_exp_f32_e32 v135, v135
	v_exp_f32_e32 v148, v148
	v_exp_f32_e32 v136, v136
	v_exp_f32_e32 v149, v149
	v_exp_f32_e32 v137, v137
	v_add_f32_e32 v1, 1.0, v1
	v_add_f32_e32 v150, 1.0, v134
	v_add_f32_e32 v141, 1.0, v141
	v_add_f32_e32 v151, 1.0, v135
	v_add_f32_e32 v148, 1.0, v148
	v_add_f32_e32 v174, 1.0, v136
	v_add_f32_e32 v149, 1.0, v149
	v_add_f32_e32 v175, 1.0, v137
	v_rcp_f32_e32 v134, v1
	v_rcp_f32_e32 v135, v150
	v_rcp_f32_e32 v136, v141
	v_rcp_f32_e32 v137, v151
	v_rcp_f32_e32 v148, v148
	v_rcp_f32_e32 v150, v149
	v_rcp_f32_e32 v151, v175
	v_rcp_f32_e32 v149, v174
	v_pk_mul_f32 v[136:137], v[26:27], v[136:137]
	v_pk_mul_f32 v[134:135], v[24:25], v[134:135]
	v_pk_mul_f32 v[150:151], v[22:23], v[150:151]
	v_pk_mul_f32 v[148:149], v[20:21], v[148:149]
	v_cvt_pk_bf16_f32 v134, v134, v135
	v_cvt_pk_bf16_f32 v135, v136, v137
	s_nop 0
	v_cvt_pk_bf16_f32 v136, v148, v149
	v_cvt_pk_bf16_f32 v137, v150, v151
	global_store_dwordx4 v[138:139], v[134:137], off
	s_nop 1
	v_lshl_add_u64 v[138:139], v[142:143], 0, s[40:41]
	v_lshl_add_u64 v[146:147], s[6:7], 0, v[138:139]
	v_lshl_add_u64 v[138:139], s[16:17], 0, v[138:139]
	s_waitcnt vmcnt(3)
	v_lshlrev_b32_e32 v1, 16, v242
	v_and_b32_e32 v134, 0xffff0000, v242
	v_lshlrev_b32_e32 v141, 16, v243
	v_and_b32_e32 v135, 0xffff0000, v243
	v_lshlrev_b32_e32 v148, 16, v244
	v_and_b32_e32 v136, 0xffff0000, v244
	v_lshlrev_b32_e32 v149, 16, v245
	v_and_b32_e32 v137, 0xffff0000, v245
	v_max_f32_e32 v1, v1, v1
	v_max_f32_e32 v134, v134, v134
	v_max_f32_e32 v141, v141, v141
	v_max_f32_e32 v135, v135, v135
	v_max_f32_e32 v148, v148, v148
	v_max_f32_e32 v136, v136, v136
	v_max_f32_e32 v149, v149, v149
	v_max_f32_e32 v137, v137, v137
	v_max_f32_e32 v1, 0xc1f00000, v1
	v_max_f32_e32 v134, 0xc1f00000, v134
	v_max_f32_e32 v141, 0xc1f00000, v141
	v_max_f32_e32 v135, 0xc1f00000, v135
	v_max_f32_e32 v148, 0xc1f00000, v148
	v_max_f32_e32 v136, 0xc1f00000, v136
	v_max_f32_e32 v149, 0xc1f00000, v149
	v_max_f32_e32 v137, 0xc1f00000, v137
	v_mul_f32_e32 v1, 0xbfb8aa3b, v1
	v_mul_f32_e32 v134, 0xbfb8aa3b, v134
	v_mul_f32_e32 v141, 0xbfb8aa3b, v141
	v_mul_f32_e32 v135, 0xbfb8aa3b, v135
	v_mul_f32_e32 v148, 0xbfb8aa3b, v148
	v_mul_f32_e32 v136, 0xbfb8aa3b, v136
	v_mul_f32_e32 v149, 0xbfb8aa3b, v149
	v_mul_f32_e32 v137, 0xbfb8aa3b, v137
	v_exp_f32_e32 v1, v1
	v_exp_f32_e32 v134, v134
	v_exp_f32_e32 v141, v141
	v_exp_f32_e32 v135, v135
	v_exp_f32_e32 v148, v148
	v_exp_f32_e32 v136, v136
	v_exp_f32_e32 v149, v149
	v_exp_f32_e32 v137, v137
	v_add_f32_e32 v1, 1.0, v1
	v_add_f32_e32 v150, 1.0, v134
	v_add_f32_e32 v141, 1.0, v141
	v_add_f32_e32 v151, 1.0, v135
	v_add_f32_e32 v148, 1.0, v148
	v_add_f32_e32 v174, 1.0, v136
	v_add_f32_e32 v149, 1.0, v149
	v_add_f32_e32 v175, 1.0, v137
	v_rcp_f32_e32 v134, v1
	v_rcp_f32_e32 v135, v150
	v_rcp_f32_e32 v136, v141
	v_rcp_f32_e32 v137, v151
	v_rcp_f32_e32 v148, v148
	v_rcp_f32_e32 v150, v149
	v_rcp_f32_e32 v151, v175
	v_rcp_f32_e32 v149, v174
	v_pk_mul_f32 v[136:137], v[50:51], v[136:137]
	v_pk_mul_f32 v[134:135], v[48:49], v[134:135]
	v_pk_mul_f32 v[150:151], v[46:47], v[150:151]
	v_pk_mul_f32 v[148:149], v[44:45], v[148:149]
	v_cvt_pk_bf16_f32 v134, v134, v135
	v_cvt_pk_bf16_f32 v135, v136, v137
	s_nop 0
	v_cvt_pk_bf16_f32 v136, v148, v149
	v_cvt_pk_bf16_f32 v137, v150, v151
	global_store_dwordx4 v[144:145], v[134:137], off
	s_nop 1
	v_lshl_add_u64 v[144:145], v[142:143], 0, s[42:43]
	v_lshl_add_u64 v[146:147], s[6:7], 0, v[144:145]
	v_lshl_add_u64 v[144:145], s[16:17], 0, v[144:145]
	s_waitcnt vmcnt(2)
; __device__ __forceinline__ float bf_lo(unsigned w) { return __uint_as_float(w << 16); }
; __device__ __forceinline__ float bf_hi(unsigned w) { return __uint_as_float(w & 0xffff0000u); }
; __device__ __forceinline__ float sigm(float x) { return __builtin_amdgcn_rcpf(1.0f + __builtin_amdgcn_exp2f(-1.4426950408889634f * x)); }
; __device__ __forceinline__ u32x4 pack8(f32x4 a, f32x4 b) { u32x4 w; w.x = cvt_pk_bf16(a[0], a[1]); w.y = cvt_pk_bf16(a[2], a[3]); w.z = cvt_pk_bf16(b[0], b[1]); w.w = cvt_pk_bf16(b[2], b[3]); return w; }
;     __device__ __forceinline__ void operator()(const f32x4 (&acc)[2][2][4][2], const Unit& u, int wr, int wc, int fr, int fq) const {
;     ...
;                 for (int bj = 0; bj < 2; ++bj) { const size_t o = ro + bj * HALF; const u32x4 b = *(const u32x4*)(GBr + o);
;                     f32x4 s0, s1; s0[0] = sigm(fmaxf(bf_lo(b.x), -30.f)); s0[1] = sigm(fmaxf(bf_hi(b.x), -30.f)); s0[2] = sigm(fmaxf(bf_lo(b.y), -30.f)); s0[3] = sigm(fmaxf(bf_hi(b.y), -30.f));
;                     s1[0] = sigm(fmaxf(bf_lo(b.z), -30.f)); s1[1] = sigm(fmaxf(bf_hi(b.z), -30.f)); s1[2] = sigm(fmaxf(bf_lo(b.w), -30.f)); s1[3] = sigm(fmaxf(bf_hi(b.w), -30.f));
;                     *(u32x4*)(Mx + o) = pack8(s0 * acc[ai][bj][m][0], s1 * acc[ai][bj][m][1]); } }
	v_lshlrev_b32_e32 v1, 16, v246
	v_and_b32_e32 v134, 0xffff0000, v246
	v_lshlrev_b32_e32 v141, 16, v247
	v_and_b32_e32 v135, 0xffff0000, v247
	v_lshlrev_b32_e32 v148, 16, v248
	v_and_b32_e32 v136, 0xffff0000, v248
	v_lshlrev_b32_e32 v149, 16, v249
	v_and_b32_e32 v137, 0xffff0000, v249
	v_max_f32_e32 v1, v1, v1
	v_max_f32_e32 v134, v134, v134
	v_max_f32_e32 v141, v141, v141
	v_max_f32_e32 v135, v135, v135
	v_max_f32_e32 v148, v148, v148
	v_max_f32_e32 v136, v136, v136
	v_max_f32_e32 v149, v149, v149
	v_max_f32_e32 v137, v137, v137
	v_max_f32_e32 v1, 0xc1f00000, v1
	v_max_f32_e32 v134, 0xc1f00000, v134
	v_max_f32_e32 v141, 0xc1f00000, v141
	v_max_f32_e32 v135, 0xc1f00000, v135
	v_max_f32_e32 v148, 0xc1f00000, v148
	v_max_f32_e32 v136, 0xc1f00000, v136
	v_max_f32_e32 v149, 0xc1f00000, v149
	v_max_f32_e32 v137, 0xc1f00000, v137
	v_mul_f32_e32 v1, 0xbfb8aa3b, v1
	v_mul_f32_e32 v134, 0xbfb8aa3b, v134
	v_mul_f32_e32 v141, 0xbfb8aa3b, v141
	v_mul_f32_e32 v135, 0xbfb8aa3b, v135
	v_mul_f32_e32 v148, 0xbfb8aa3b, v148
	v_mul_f32_e32 v136, 0xbfb8aa3b, v136
	v_mul_f32_e32 v149, 0xbfb8aa3b, v149
	v_mul_f32_e32 v137, 0xbfb8aa3b, v137
	v_exp_f32_e32 v1, v1
	v_exp_f32_e32 v134, v134
	v_exp_f32_e32 v141, v141
	v_exp_f32_e32 v135, v135
	v_exp_f32_e32 v148, v148
	v_exp_f32_e32 v136, v136
	v_exp_f32_e32 v149, v149
	v_exp_f32_e32 v137, v137
	v_add_f32_e32 v1, 1.0, v1
	v_add_f32_e32 v150, 1.0, v134
	v_add_f32_e32 v141, 1.0, v141
	v_add_f32_e32 v151, 1.0, v135
	v_add_f32_e32 v148, 1.0, v148
	v_add_f32_e32 v174, 1.0, v136
	v_add_f32_e32 v149, 1.0, v149
	v_add_f32_e32 v175, 1.0, v137
	v_rcp_f32_e32 v134, v1
	v_rcp_f32_e32 v135, v150
	v_rcp_f32_e32 v136, v141
	v_rcp_f32_e32 v137, v151
	v_rcp_f32_e32 v148, v148
	v_rcp_f32_e32 v150, v149
	v_rcp_f32_e32 v151, v175
	v_rcp_f32_e32 v149, v174
	v_pk_mul_f32 v[136:137], v[18:19], v[136:137]
	v_pk_mul_f32 v[134:135], v[16:17], v[134:135]
	v_pk_mul_f32 v[150:151], v[14:15], v[150:151]
	v_pk_mul_f32 v[148:149], v[12:13], v[148:149]
	v_cvt_pk_bf16_f32 v134, v134, v135
	v_cvt_pk_bf16_f32 v135, v136, v137
	s_nop 0
	v_cvt_pk_bf16_f32 v136, v148, v149
	v_cvt_pk_bf16_f32 v137, v150, v151
	global_store_dwordx4 v[138:139], v[134:137], off
	s_nop 1
	v_lshl_add_u64 v[138:139], v[142:143], 0, s[44:45]
	v_lshl_add_u64 v[146:147], s[6:7], 0, v[138:139]
	v_lshl_add_u64 v[138:139], s[16:17], 0, v[138:139]
	s_waitcnt vmcnt(1)
	v_lshlrev_b32_e32 v1, 16, v252
	v_and_b32_e32 v134, 0xffff0000, v252
	v_lshlrev_b32_e32 v141, 16, v253
	v_and_b32_e32 v135, 0xffff0000, v253
	v_lshlrev_b32_e32 v148, 16, v254
	v_and_b32_e32 v136, 0xffff0000, v254
	v_lshlrev_b32_e32 v149, 16, v255
	v_and_b32_e32 v137, 0xffff0000, v255
	v_max_f32_e32 v1, v1, v1
	v_max_f32_e32 v134, v134, v134
	v_max_f32_e32 v141, v141, v141
	v_max_f32_e32 v135, v135, v135
	v_max_f32_e32 v148, v148, v148
	v_max_f32_e32 v136, v136, v136
	v_max_f32_e32 v149, v149, v149
	v_max_f32_e32 v137, v137, v137
	v_max_f32_e32 v1, 0xc1f00000, v1
	v_max_f32_e32 v134, 0xc1f00000, v134
	v_max_f32_e32 v141, 0xc1f00000, v141
	v_max_f32_e32 v135, 0xc1f00000, v135
	v_max_f32_e32 v148, 0xc1f00000, v148
	v_max_f32_e32 v136, 0xc1f00000, v136
	v_max_f32_e32 v149, 0xc1f00000, v149
	v_max_f32_e32 v137, 0xc1f00000, v137
	v_mul_f32_e32 v1, 0xbfb8aa3b, v1
	v_mul_f32_e32 v134, 0xbfb8aa3b, v134
	v_mul_f32_e32 v141, 0xbfb8aa3b, v141
	v_mul_f32_e32 v135, 0xbfb8aa3b, v135
	v_mul_f32_e32 v148, 0xbfb8aa3b, v148
	v_mul_f32_e32 v136, 0xbfb8aa3b, v136
	v_mul_f32_e32 v149, 0xbfb8aa3b, v149
	v_mul_f32_e32 v137, 0xbfb8aa3b, v137
	v_exp_f32_e32 v1, v1
	v_exp_f32_e32 v134, v134
	v_exp_f32_e32 v141, v141
	v_exp_f32_e32 v135, v135
	v_exp_f32_e32 v148, v148
	v_exp_f32_e32 v136, v136
	v_exp_f32_e32 v149, v149
	v_exp_f32_e32 v137, v137
	v_add_f32_e32 v1, 1.0, v1
	v_add_f32_e32 v150, 1.0, v134
	v_add_f32_e32 v141, 1.0, v141
	v_add_f32_e32 v151, 1.0, v135
	v_add_f32_e32 v148, 1.0, v148
	v_add_f32_e32 v174, 1.0, v136
	v_add_f32_e32 v149, 1.0, v149
	v_add_f32_e32 v175, 1.0, v137
	v_rcp_f32_e32 v134, v1
	v_rcp_f32_e32 v135, v150
	v_rcp_f32_e32 v136, v141
	v_rcp_f32_e32 v137, v151
	v_rcp_f32_e32 v148, v148
	v_rcp_f32_e32 v150, v149
	v_rcp_f32_e32 v151, v175
	v_rcp_f32_e32 v149, v174
	v_pk_mul_f32 v[136:137], v[42:43], v[136:137]
	v_pk_mul_f32 v[134:135], v[40:41], v[134:135]
	v_pk_mul_f32 v[150:151], v[38:39], v[150:151]
	v_pk_mul_f32 v[148:149], v[36:37], v[148:149]
	v_cvt_pk_bf16_f32 v134, v134, v135
	v_cvt_pk_bf16_f32 v135, v136, v137
	s_nop 0
	v_cvt_pk_bf16_f32 v136, v148, v149
	v_cvt_pk_bf16_f32 v137, v150, v151
	global_store_dwordx4 v[144:145], v[134:137], off
	s_nop 1
	s_waitcnt vmcnt(0)
	v_lshlrev_b32_e32 v1, 16, v184
	v_and_b32_e32 v134, 0xffff0000, v184
	v_lshlrev_b32_e32 v141, 16, v185
	v_and_b32_e32 v135, 0xffff0000, v185
	v_lshlrev_b32_e32 v144, 16, v186
	v_and_b32_e32 v136, 0xffff0000, v186
	v_lshlrev_b32_e32 v145, 16, v187
	v_and_b32_e32 v137, 0xffff0000, v187
	v_max_f32_e32 v1, v1, v1
	v_max_f32_e32 v134, v134, v134
	v_max_f32_e32 v141, v141, v141
	v_max_f32_e32 v135, v135, v135
	v_max_f32_e32 v144, v144, v144
	v_max_f32_e32 v136, v136, v136
	v_max_f32_e32 v145, v145, v145
	v_max_f32_e32 v137, v137, v137
	v_max_f32_e32 v1, 0xc1f00000, v1
	v_max_f32_e32 v134, 0xc1f00000, v134
	v_max_f32_e32 v141, 0xc1f00000, v141
	v_max_f32_e32 v135, 0xc1f00000, v135
	v_max_f32_e32 v144, 0xc1f00000, v144
	v_max_f32_e32 v136, 0xc1f00000, v136
	v_max_f32_e32 v145, 0xc1f00000, v145
	v_max_f32_e32 v137, 0xc1f00000, v137
	v_mul_f32_e32 v1, 0xbfb8aa3b, v1
	v_mul_f32_e32 v134, 0xbfb8aa3b, v134
	v_mul_f32_e32 v141, 0xbfb8aa3b, v141
	v_mul_f32_e32 v135, 0xbfb8aa3b, v135
	v_mul_f32_e32 v144, 0xbfb8aa3b, v144
	v_mul_f32_e32 v136, 0xbfb8aa3b, v136
	v_mul_f32_e32 v145, 0xbfb8aa3b, v145
	v_mul_f32_e32 v137, 0xbfb8aa3b, v137
	v_exp_f32_e32 v1, v1
	v_exp_f32_e32 v134, v134
	v_exp_f32_e32 v141, v141
	v_exp_f32_e32 v135, v135
	v_exp_f32_e32 v144, v144
	v_exp_f32_e32 v136, v136
	v_exp_f32_e32 v145, v145
	v_exp_f32_e32 v137, v137
	v_add_f32_e32 v1, 1.0, v1
	v_add_f32_e32 v146, 1.0, v134
	v_add_f32_e32 v141, 1.0, v141
	v_add_f32_e32 v147, 1.0, v135
	v_add_f32_e32 v144, 1.0, v144
	v_add_f32_e32 v148, 1.0, v136
	v_add_f32_e32 v145, 1.0, v145
	v_add_f32_e32 v149, 1.0, v137
	v_rcp_f32_e32 v134, v1
	v_rcp_f32_e32 v135, v146
	v_rcp_f32_e32 v136, v141
	v_rcp_f32_e32 v137, v147
	v_rcp_f32_e32 v144, v144
	v_rcp_f32_e32 v146, v145
	v_rcp_f32_e32 v147, v149
	v_rcp_f32_e32 v145, v148
	v_pk_mul_f32 v[136:137], v[10:11], v[136:137]
	v_pk_mul_f32 v[134:135], v[8:9], v[134:135]
	v_pk_mul_f32 v[146:147], v[6:7], v[146:147]
	v_pk_mul_f32 v[144:145], v[4:5], v[144:145]
	v_cvt_pk_bf16_f32 v134, v134, v135
	v_cvt_pk_bf16_f32 v135, v136, v137
	s_nop 0
	v_cvt_pk_bf16_f32 v136, v144, v145
	v_cvt_pk_bf16_f32 v137, v146, v147
	global_store_dwordx4 v[138:139], v[134:137], off
	s_cbranch_execnz .LBB0_1035
